# Strategy 7 instruction selection: MLA attention unmasked tile bodies, 32 v_fmamk -> 16 v_pk_fma_f32 and 32-add serial row-sum -> 15 v_pk_add_f32 + 1 (exps in place, 4 temporaries)
# baseline (speedup 1.0000x reference)
; DI unsigned pack2(float a, float b) { unsigned r; asm("v_cvt_pk_bf16_f32 %0, %1, %2\n\ts_nop 1" : "=v"(r) : "v"(a), "v"(b)); return r; }
; #define MFMA32(a, b, c) __builtin_amdgcn_mfma_f32_32x32x16_bf16((a), (b), (c), 0, 0, 0)
; template <int DQK, bool WIN>
; DI void attn_item(const u16* __restrict__ Qb, int ldq, const u16* __restrict__ Kb, int ldk, const u16* __restrict__ Vtb, int qb,
;                   float qscale, float sink2, const u16* __restrict__ zb, int ldz, u16* __restrict__ ob, int ldo, u16* lds) {
;     ...
;       const float nb = -mn * qscale;
;       float ps = 0.f;
; #pragma unroll
;       for (int kb = 0; kb < 2; ++kb)
; #pragma unroll
;         for (int i = 0; i < 16; ++i) { float pv = __builtin_amdgcn_exp2f(fmaf(st[kb][i], qscale, nb)); st[kb][i] = pv; ps += pv; }
;       lsum += ps;
; #pragma unroll
;       for (int kb = 0; kb < 2; ++kb)
; #pragma unroll
;         for (int s2 = 0; s2 < 2; ++s2) {
;           union { bf16x8 v; unsigned u[4]; } pf;
; #pragma unroll
;           for (int j = 0; j < 4; ++j) pf.u[j] = pack2(st[kb][8 * s2 + 2 * j], st[kb][8 * s2 + 2 * j + 1]);
; #pragma unroll
;           for (int vb = 0; vb < 2; ++vb) {
;             const bf16x8 vf = *(const bf16x8*)(vs + (vb * 32 + r) * 72 + (kb * 2 + s2) * 16 + hh * 8);
;             o[vb] = MFMA32(vf, pf.v, o[vb]);
;           }
;         }
.LBB0_243:
	ds_read_b128 v[186:189], v156 offset:13312
	ds_read_b128 v[190:193], v156 offset:13344
	ds_read_b128 v[194:197], v156 offset:17920
	ds_read_b128 v[198:201], v156 offset:17952
	ds_read_b128 v[202:205], v156 offset:13376
	ds_read_b128 v[206:209], v156 offset:17984
	ds_read_b128 v[210:213], v156 offset:13408
	ds_read_b128 v[214:217], v156 offset:18016
	v_mul_f32_e32 v158, 0xbe16c740, v0
	s_mov_b32 s98, 0x3e16c740
	v_pk_fma_f32 v[50:51], v[50:51], s[98:99], v[158:159] op_sel_hi:[1,0,0]
	v_pk_fma_f32 v[52:53], v[52:53], s[98:99], v[158:159] op_sel_hi:[1,0,0]
	v_pk_fma_f32 v[54:55], v[54:55], s[98:99], v[158:159] op_sel_hi:[1,0,0]
	v_pk_fma_f32 v[56:57], v[56:57], s[98:99], v[158:159] op_sel_hi:[1,0,0]
	v_pk_fma_f32 v[58:59], v[58:59], s[98:99], v[158:159] op_sel_hi:[1,0,0]
	v_pk_fma_f32 v[60:61], v[60:61], s[98:99], v[158:159] op_sel_hi:[1,0,0]
	v_pk_fma_f32 v[62:63], v[62:63], s[98:99], v[158:159] op_sel_hi:[1,0,0]
	v_pk_fma_f32 v[64:65], v[64:65], s[98:99], v[158:159] op_sel_hi:[1,0,0]
	v_pk_fma_f32 v[34:35], v[34:35], s[98:99], v[158:159] op_sel_hi:[1,0,0]
	v_pk_fma_f32 v[36:37], v[36:37], s[98:99], v[158:159] op_sel_hi:[1,0,0]
	v_pk_fma_f32 v[38:39], v[38:39], s[98:99], v[158:159] op_sel_hi:[1,0,0]
	v_pk_fma_f32 v[40:41], v[40:41], s[98:99], v[158:159] op_sel_hi:[1,0,0]
	v_pk_fma_f32 v[42:43], v[42:43], s[98:99], v[158:159] op_sel_hi:[1,0,0]
	v_pk_fma_f32 v[44:45], v[44:45], s[98:99], v[158:159] op_sel_hi:[1,0,0]
	v_pk_fma_f32 v[46:47], v[46:47], s[98:99], v[158:159] op_sel_hi:[1,0,0]
	v_pk_fma_f32 v[48:49], v[48:49], s[98:99], v[158:159] op_sel_hi:[1,0,0]
	v_exp_f32_e32 v50, v50
	v_exp_f32_e32 v51, v51
	v_exp_f32_e32 v52, v52
	v_exp_f32_e32 v53, v53
	v_exp_f32_e32 v54, v54
	v_pk_add_f32 v[164:165], v[50:51], v[52:53]
	v_exp_f32_e32 v55, v55
	v_exp_f32_e32 v56, v56
	v_pk_add_f32 v[164:165], v[164:165], v[54:55]
	v_exp_f32_e32 v57, v57
	v_exp_f32_e32 v58, v58
	v_pk_add_f32 v[164:165], v[164:165], v[56:57]
	v_exp_f32_e32 v59, v59
	v_exp_f32_e32 v60, v60
	v_pk_add_f32 v[164:165], v[164:165], v[58:59]
	v_exp_f32_e32 v61, v61
	v_exp_f32_e32 v62, v62
	v_pk_add_f32 v[164:165], v[164:165], v[60:61]
	v_exp_f32_e32 v63, v63
	v_exp_f32_e32 v64, v64
	v_pk_add_f32 v[164:165], v[164:165], v[62:63]
	v_exp_f32_e32 v65, v65
	v_exp_f32_e32 v158, v34
	v_pk_add_f32 v[164:165], v[164:165], v[64:65]
	v_exp_f32_e32 v159, v35
	v_exp_f32_e32 v160, v36
	v_pk_add_f32 v[164:165], v[164:165], v[158:159]
	v_exp_f32_e32 v161, v37
	v_exp_f32_e32 v38, v38
	v_pk_add_f32 v[164:165], v[164:165], v[160:161]
	v_exp_f32_e32 v39, v39
	v_exp_f32_e32 v40, v40
	v_pk_add_f32 v[164:165], v[164:165], v[38:39]
	v_exp_f32_e32 v41, v41
	v_exp_f32_e32 v42, v42
	v_pk_add_f32 v[164:165], v[164:165], v[40:41]
	v_exp_f32_e32 v43, v43
	v_exp_f32_e32 v44, v44
	v_pk_add_f32 v[164:165], v[164:165], v[42:43]
	v_exp_f32_e32 v45, v45
	v_exp_f32_e32 v46, v46
	v_pk_add_f32 v[164:165], v[164:165], v[44:45]
	v_exp_f32_e32 v47, v47
	v_exp_f32_e32 v48, v48
	v_pk_add_f32 v[164:165], v[164:165], v[46:47]
	v_exp_f32_e32 v49, v49
	s_nop 0
	v_pk_add_f32 v[164:165], v[164:165], v[48:49]
	s_nop 0
	v_add_f32_e32 v164, v164, v165
	v_add_f32_e32 v142, v164, v142
	v_cvt_pk_bf16_f32 v34, v50, v51
	v_cvt_pk_bf16_f32 v35, v52, v53
	v_cvt_pk_bf16_f32 v36, v54, v55
	v_cvt_pk_bf16_f32 v37, v56, v57
	v_mov_b32_e32 v157, v0
	s_waitcnt lgkmcnt(7)
	v_mfma_f32_32x32x16_bf16 v[18:33], v[186:189], v[34:37], v[18:33]
	s_waitcnt lgkmcnt(5)
	v_mfma_f32_32x32x16_bf16 v[2:17], v[194:197], v[34:37], v[2:17]
	v_cvt_pk_bf16_f32 v34, v58, v59
	v_cvt_pk_bf16_f32 v35, v60, v61
	v_cvt_pk_bf16_f32 v36, v62, v63
	v_cvt_pk_bf16_f32 v37, v64, v65
	s_waitcnt lgkmcnt(4)
	s_nop 0
	v_mfma_f32_32x32x16_bf16 v[2:17], v[198:201], v[34:37], v[2:17]
	v_mfma_f32_32x32x16_bf16 v[18:33], v[190:193], v[34:37], v[18:33]
	v_cvt_pk_bf16_f32 v34, v158, v159
	v_cvt_pk_bf16_f32 v35, v160, v161
	v_cvt_pk_bf16_f32 v36, v38, v39
	v_cvt_pk_bf16_f32 v37, v40, v41
	s_waitcnt lgkmcnt(3)
	s_nop 0
	v_mfma_f32_32x32x16_bf16 v[18:33], v[202:205], v[34:37], v[18:33]
	s_waitcnt lgkmcnt(2)
	v_mfma_f32_32x32x16_bf16 v[2:17], v[206:209], v[34:37], v[2:17]
	v_cvt_pk_bf16_f32 v34, v42, v43
	v_cvt_pk_bf16_f32 v35, v44, v45
	v_cvt_pk_bf16_f32 v36, v46, v47
	v_cvt_pk_bf16_f32 v37, v48, v49
	s_waitcnt lgkmcnt(1)
	s_nop 0
	v_mfma_f32_32x32x16_bf16 v[18:33], v[210:213], v[34:37], v[18:33]
	s_waitcnt lgkmcnt(0)
	v_mfma_f32_32x32x16_bf16 v[2:17], v[214:217], v[34:37], v[2:17]

; DI unsigned pack2(float a, float b) { unsigned r; asm("v_cvt_pk_bf16_f32 %0, %1, %2\n\ts_nop 1" : "=v"(r) : "v"(a), "v"(b)); return r; }
; #define MFMA32(a, b, c) __builtin_amdgcn_mfma_f32_32x32x16_bf16((a), (b), (c), 0, 0, 0)
; template <int DQK, bool WIN>
; DI void attn_item(const u16* __restrict__ Qb, int ldq, const u16* __restrict__ Kb, int ldk, const u16* __restrict__ Vtb, int qb,
;                   float qscale, float sink2, const u16* __restrict__ zb, int ldz, u16* __restrict__ ob, int ldo, u16* lds) {
;     ...
;       const float nb = -mn * qscale;
;       float ps = 0.f;
; #pragma unroll
;       for (int kb = 0; kb < 2; ++kb)
; #pragma unroll
;         for (int i = 0; i < 16; ++i) { float pv = __builtin_amdgcn_exp2f(fmaf(st[kb][i], qscale, nb)); st[kb][i] = pv; ps += pv; }
;       lsum += ps;
; #pragma unroll
;       for (int kb = 0; kb < 2; ++kb)
; #pragma unroll
;         for (int s2 = 0; s2 < 2; ++s2) {
;           union { bf16x8 v; unsigned u[4]; } pf;
; #pragma unroll
;           for (int j = 0; j < 4; ++j) pf.u[j] = pack2(st[kb][8 * s2 + 2 * j], st[kb][8 * s2 + 2 * j + 1]);
; #pragma unroll
;           for (int vb = 0; vb < 2; ++vb) {
;             const bf16x8 vf = *(const bf16x8*)(vs + (vb * 32 + r) * 72 + (kb * 2 + s2) * 16 + hh * 8);
;             o[vb] = MFMA32(vf, pf.v, o[vb]);
;           }
;         }
.LBB0_261:
	ds_read_b128 v[186:189], v156 offset:35840
	ds_read_b128 v[190:193], v156 offset:35872
	ds_read_b128 v[194:197], v156 offset:40448
	ds_read_b128 v[198:201], v156 offset:40480
	ds_read_b128 v[202:205], v156 offset:35904
	ds_read_b128 v[206:209], v156 offset:40512
	ds_read_b128 v[210:213], v156 offset:35936
	ds_read_b128 v[214:217], v156 offset:40544
	v_mul_f32_e32 v158, 0xbe16c740, v0
	s_mov_b32 s98, 0x3e16c740
	v_pk_fma_f32 v[34:35], v[34:35], s[98:99], v[158:159] op_sel_hi:[1,0,0]
	v_pk_fma_f32 v[36:37], v[36:37], s[98:99], v[158:159] op_sel_hi:[1,0,0]
	v_pk_fma_f32 v[38:39], v[38:39], s[98:99], v[158:159] op_sel_hi:[1,0,0]
	v_pk_fma_f32 v[40:41], v[40:41], s[98:99], v[158:159] op_sel_hi:[1,0,0]
	v_pk_fma_f32 v[42:43], v[42:43], s[98:99], v[158:159] op_sel_hi:[1,0,0]
	v_pk_fma_f32 v[44:45], v[44:45], s[98:99], v[158:159] op_sel_hi:[1,0,0]
	v_pk_fma_f32 v[46:47], v[46:47], s[98:99], v[158:159] op_sel_hi:[1,0,0]
	v_pk_fma_f32 v[48:49], v[48:49], s[98:99], v[158:159] op_sel_hi:[1,0,0]
	v_pk_fma_f32 v[50:51], v[50:51], s[98:99], v[158:159] op_sel_hi:[1,0,0]
	v_pk_fma_f32 v[52:53], v[52:53], s[98:99], v[158:159] op_sel_hi:[1,0,0]
	v_pk_fma_f32 v[54:55], v[54:55], s[98:99], v[158:159] op_sel_hi:[1,0,0]
	v_pk_fma_f32 v[56:57], v[56:57], s[98:99], v[158:159] op_sel_hi:[1,0,0]
	v_pk_fma_f32 v[58:59], v[58:59], s[98:99], v[158:159] op_sel_hi:[1,0,0]
	v_pk_fma_f32 v[60:61], v[60:61], s[98:99], v[158:159] op_sel_hi:[1,0,0]
	v_pk_fma_f32 v[62:63], v[62:63], s[98:99], v[158:159] op_sel_hi:[1,0,0]
	v_pk_fma_f32 v[64:65], v[64:65], s[98:99], v[158:159] op_sel_hi:[1,0,0]
	v_exp_f32_e32 v34, v34
	v_exp_f32_e32 v35, v35
	v_exp_f32_e32 v36, v36
	v_exp_f32_e32 v37, v37
	v_exp_f32_e32 v38, v38
	v_pk_add_f32 v[164:165], v[34:35], v[36:37]
	v_exp_f32_e32 v39, v39
	v_exp_f32_e32 v40, v40
	v_pk_add_f32 v[164:165], v[164:165], v[38:39]
	v_exp_f32_e32 v41, v41
	v_exp_f32_e32 v42, v42
	v_pk_add_f32 v[164:165], v[164:165], v[40:41]
	v_exp_f32_e32 v43, v43
	v_exp_f32_e32 v44, v44
	v_pk_add_f32 v[164:165], v[164:165], v[42:43]
	v_exp_f32_e32 v45, v45
	v_exp_f32_e32 v46, v46
	v_pk_add_f32 v[164:165], v[164:165], v[44:45]
	v_exp_f32_e32 v47, v47
	v_exp_f32_e32 v48, v48
	v_pk_add_f32 v[164:165], v[164:165], v[46:47]
	v_exp_f32_e32 v49, v49
	v_exp_f32_e32 v158, v50
	v_pk_add_f32 v[164:165], v[164:165], v[48:49]
	v_exp_f32_e32 v159, v51
	v_exp_f32_e32 v160, v52
	v_pk_add_f32 v[164:165], v[164:165], v[158:159]
	v_exp_f32_e32 v161, v53
	v_exp_f32_e32 v54, v54
	v_pk_add_f32 v[164:165], v[164:165], v[160:161]
	v_exp_f32_e32 v55, v55
	v_exp_f32_e32 v56, v56
	v_pk_add_f32 v[164:165], v[164:165], v[54:55]
	v_exp_f32_e32 v57, v57
	v_exp_f32_e32 v58, v58
	v_pk_add_f32 v[164:165], v[164:165], v[56:57]
	v_exp_f32_e32 v59, v59
	v_exp_f32_e32 v60, v60
	v_pk_add_f32 v[164:165], v[164:165], v[58:59]
	v_exp_f32_e32 v61, v61
	v_exp_f32_e32 v62, v62
	v_pk_add_f32 v[164:165], v[164:165], v[60:61]
	v_exp_f32_e32 v63, v63
	v_exp_f32_e32 v64, v64
	v_pk_add_f32 v[164:165], v[164:165], v[62:63]
	v_exp_f32_e32 v65, v65
	s_nop 0
	v_pk_add_f32 v[164:165], v[164:165], v[64:65]
	s_nop 0
	v_add_f32_e32 v164, v164, v165
	v_add_f32_e32 v142, v164, v142
	v_cvt_pk_bf16_f32 v50, v34, v35
	v_cvt_pk_bf16_f32 v51, v36, v37
	v_cvt_pk_bf16_f32 v52, v38, v39
	v_cvt_pk_bf16_f32 v53, v40, v41
	s_waitcnt lgkmcnt(7)
	s_nop 0
	v_mfma_f32_32x32x16_bf16 v[18:33], v[186:189], v[50:53], v[18:33]
	s_waitcnt lgkmcnt(5)
	v_mfma_f32_32x32x16_bf16 v[2:17], v[194:197], v[50:53], v[2:17]
	v_cvt_pk_bf16_f32 v50, v42, v43
	v_cvt_pk_bf16_f32 v51, v44, v45
	v_cvt_pk_bf16_f32 v52, v46, v47
	v_cvt_pk_bf16_f32 v53, v48, v49
	s_waitcnt lgkmcnt(4)
	s_nop 0
	v_mfma_f32_32x32x16_bf16 v[2:17], v[198:201], v[50:53], v[2:17]
	v_mfma_f32_32x32x16_bf16 v[18:33], v[190:193], v[50:53], v[18:33]
	v_cvt_pk_bf16_f32 v50, v158, v159
	v_cvt_pk_bf16_f32 v51, v160, v161
	v_cvt_pk_bf16_f32 v52, v54, v55
	v_cvt_pk_bf16_f32 v53, v56, v57
	v_mov_b32_e32 v157, v0
	s_waitcnt lgkmcnt(3)
	v_mfma_f32_32x32x16_bf16 v[18:33], v[202:205], v[50:53], v[18:33]
	s_waitcnt lgkmcnt(2)
	v_mfma_f32_32x32x16_bf16 v[2:17], v[206:209], v[50:53], v[2:17]
	v_cvt_pk_bf16_f32 v50, v58, v59
	v_cvt_pk_bf16_f32 v51, v60, v61
	v_cvt_pk_bf16_f32 v52, v62, v63
	v_cvt_pk_bf16_f32 v53, v64, v65
	s_waitcnt lgkmcnt(1)
	s_nop 0
	v_mfma_f32_32x32x16_bf16 v[18:33], v[210:213], v[50:53], v[18:33]
	s_waitcnt lgkmcnt(0)
	v_mfma_f32_32x32x16_bf16 v[2:17], v[214:217], v[50:53], v[2:17]
